# final seam prefetch: counted vmcnt(8) at body top so the previous pair's stores stay in flight; reload path drains itself
# speedup vs baseline: 1.0099x; 1.0037x over previous
.LBB0_1210:
	s_or_b64 exec, exec, s[0:1]
	s_waitcnt vmcnt(8)
	v_mov_b64_e32 v[56:57], v[200:201]
	v_mov_b64_e32 v[50:51], v[202:203]
	v_mov_b64_e32 v[48:49], v[204:205]
	v_mov_b64_e32 v[44:45], v[206:207]
	v_mov_b64_e32 v[60:61], v[208:209]
	v_mov_b64_e32 v[58:59], v[210:211]
	v_mov_b64_e32 v[54:55], v[212:213]
	v_mov_b64_e32 v[52:53], v[214:215]
	v_mov_b64_e32 v[46:47], v[216:217]
	v_mov_b64_e32 v[42:43], v[218:219]
	v_mov_b64_e32 v[40:41], v[220:221]
	v_mov_b64_e32 v[38:39], v[222:223]
	v_mov_b64_e32 v[72:73], v[224:225]
	v_mov_b64_e32 v[70:71], v[226:227]
	v_mov_b64_e32 v[68:69], v[228:229]
	v_mov_b64_e32 v[66:67], v[230:231]
	v_lshl_add_u64 v[34:35], v[34:35], 0, s[4:5]
	v_add_u32_e32 v197, 2, v148
	v_cmp_lt_i32_e32 vcc, v197, v186
	s_and_saveexec_b64 s[14:15], vcc
	s_cbranch_execz .Ls3_nopf
	v_add_co_u32_e32 v198, vcc, s11, v34
	global_load_dwordx2 v[200:201], v[34:35], off offset:-3584
	global_load_dwordx2 v[202:203], v[34:35], off offset:-3072
	global_load_dwordx2 v[204:205], v[34:35], off offset:-2560
	global_load_dwordx2 v[206:207], v[34:35], off offset:-2048
	v_addc_co_u32_e32 v199, vcc, -1, v35, vcc
	global_load_dwordx2 v[208:209], v[198:199], off offset:-3584
	global_load_dwordx2 v[210:211], v[198:199], off offset:-3072
	global_load_dwordx2 v[212:213], v[198:199], off offset:-2560
	global_load_dwordx2 v[214:215], v[198:199], off offset:-2048
	global_load_dwordx2 v[216:217], v[34:35], off offset:-1536
	global_load_dwordx2 v[218:219], v[34:35], off offset:-1024
	global_load_dwordx2 v[220:221], v[34:35], off offset:-512
	global_load_dwordx2 v[222:223], v[34:35], off
	global_load_dwordx2 v[224:225], v[198:199], off offset:-1536
	global_load_dwordx2 v[226:227], v[198:199], off offset:-1024
	global_load_dwordx2 v[228:229], v[198:199], off offset:-512
	global_load_dwordx2 v[230:231], v[198:199], off

.LBB0_1211:
	v_add_u32_e32 v62, 0xffffe000, v148
	v_ashrrev_i32_e32 v62, 12, v62
	v_add_u32_e32 v62, 1, v62
	v_cmp_lt_i32_e32 vcc, s12, v148
	s_nop 1
	v_cndmask_b32_e32 v62, 0, v62, vcc
	v_cmp_ne_u32_e32 vcc, v62, v79
	s_and_saveexec_b64 s[0:1], vcc
	s_cbranch_execz .LBB0_1210
	v_mul_i32_i24_e32 v16, 0x2400, v62
	v_ashrrev_i32_e32 v17, 31, v16
	v_lshl_add_u64 v[16:17], v[16:17], 2, s[34:35]
	v_lshl_add_u64 v[24:25], v[16:17], 0, s[8:9]
	v_mov_b32_e32 v155, v145
	v_mov_b32_e32 v153, v145
	v_lshl_add_u64 v[26:27], v[24:25], 0, v[144:145]
	v_lshl_add_u64 v[28:29], v[24:25], 0, v[154:155]
	v_lshl_add_u64 v[64:65], v[24:25], 0, v[152:153]
	v_mov_b32_e32 v151, v145
	global_load_dwordx4 v[16:19], v[26:27], off
	global_load_dwordx4 v[20:23], v[28:29], off
	v_lshl_add_u64 v[80:81], v[24:25], 0, v[150:151]
	global_load_dwordx4 v[24:27], v[64:65], off
	global_load_dwordx4 v[28:31], v[80:81], off
	v_mov_b32_e32 v79, v62
	s_waitcnt vmcnt(0)
	s_branch .LBB0_1210
